# Epi2c KVS stores use default cache policy instead of nt (so the sample MLA reads next phase may hit L2/Infinity Cache), on top of v12
# speedup vs baseline: 1.0095x; 1.0095x over previous
.LBB0_536:
	s_add_u32 s48, s45, 0xffffff80
	s_addc_u32 s49, s46, -1
	s_cmp_eq_u32 s47, 4
	s_cselect_b32 s22, s41, s45
	s_cselect_b32 s23, s7, s46
	s_cselect_b32 s25, s9, s44
	s_cselect_b32 s24, s42, s43
	s_add_u32 s18, s22, 0x80
	s_addc_u32 s19, s23, 0
	s_add_u32 s20, s24, 0x80
	s_addc_u32 s21, s25, 0
	s_add_i32 s50, 0, 0x10000
	s_add_i32 s51, 0, 0x14000
	v_add_u32_e32 v152, s50, v1
	v_add_u32_e32 v168, s51, v1
	ds_read_b128 v[140:143], v152
	ds_read_b128 v[144:147], v152 offset:1024
	ds_read_b128 v[148:151], v152 offset:2048
	ds_read_b128 v[152:155], v152 offset:3072
	ds_read_b128 v[156:159], v168
	ds_read_b128 v[160:163], v168 offset:1024
	ds_read_b128 v[164:167], v168 offset:2048
	ds_read_b128 v[168:171], v168 offset:3072
	s_add_u32 s48, s48, 0x20000
	s_addc_u32 s49, s49, 0
	v_lshl_add_u64 v[204:205], s[48:49], 0, v[2:3]
	s_add_i32 m0, s15, 0xc000
	ds_read_b128 v[172:175], v5
	ds_read_b128 v[176:179], v5 offset:1024
	ds_read_b128 v[180:183], v5 offset:2048
	ds_read_b128 v[184:187], v5 offset:3072
	ds_read_b128 v[188:191], v5 offset:4096
	ds_read_b128 v[192:195], v5 offset:5120
	ds_read_b128 v[196:199], v5 offset:6144
	ds_read_b128 v[200:203], v5 offset:7168
	global_load_lds_dwordx4 v[204:205], off
	v_lshl_add_u64 v[204:205], s[48:49], 0, v[136:137]
	s_add_i32 m0, s15, 0xe000
	s_nop 0
	global_load_lds_dwordx4 v[204:205], off
	s_waitcnt vmcnt(8)
	s_waitcnt lgkmcnt(0)
	s_barrier
	s_setprio 1
	s_waitcnt lgkmcnt(0)
	v_mfma_f32_16x16x32_bf16 v[130:133], v[140:143], v[172:175], v[130:133]
	v_mfma_f32_16x16x32_bf16 v[126:129], v[148:151], v[172:175], v[126:129]
	v_mfma_f32_16x16x32_bf16 v[122:125], v[140:143], v[180:183], v[122:125]
	v_mfma_f32_16x16x32_bf16 v[114:117], v[148:151], v[180:183], v[114:117]
	v_mfma_f32_16x16x32_bf16 v[106:109], v[140:143], v[188:191], v[106:109]
	v_mfma_f32_16x16x32_bf16 v[98:101], v[148:151], v[188:191], v[98:101]
	v_mfma_f32_16x16x32_bf16 v[90:93], v[140:143], v[196:199], v[90:93]
	v_mfma_f32_16x16x32_bf16 v[82:85], v[148:151], v[196:199], v[82:85]
	v_mfma_f32_16x16x32_bf16 v[130:133], v[144:147], v[176:179], v[130:133]
	v_mfma_f32_16x16x32_bf16 v[126:129], v[152:155], v[176:179], v[126:129]
	v_mfma_f32_16x16x32_bf16 v[122:125], v[144:147], v[184:187], v[122:125]
	v_mfma_f32_16x16x32_bf16 v[114:117], v[152:155], v[184:187], v[114:117]
	v_mfma_f32_16x16x32_bf16 v[106:109], v[144:147], v[192:195], v[106:109]
	v_mfma_f32_16x16x32_bf16 v[98:101], v[152:155], v[192:195], v[98:101]
	v_mfma_f32_16x16x32_bf16 v[90:93], v[144:147], v[200:203], v[90:93]
	v_mfma_f32_16x16x32_bf16 v[82:85], v[152:155], v[200:203], v[82:85]
	s_setprio 0
	s_setprio 1
	v_mfma_f32_16x16x32_bf16 v[118:121], v[156:159], v[172:175], v[118:121]
	v_mfma_f32_16x16x32_bf16 v[110:113], v[164:167], v[172:175], v[110:113]
	v_mfma_f32_16x16x32_bf16 v[102:105], v[156:159], v[180:183], v[102:105]
	v_mfma_f32_16x16x32_bf16 v[94:97], v[164:167], v[180:183], v[94:97]
	v_mfma_f32_16x16x32_bf16 v[86:89], v[156:159], v[188:191], v[86:89]
	v_mfma_f32_16x16x32_bf16 v[78:81], v[164:167], v[188:191], v[78:81]
	v_mfma_f32_16x16x32_bf16 v[74:77], v[156:159], v[196:199], v[74:77]
	v_mfma_f32_16x16x32_bf16 v[70:73], v[164:167], v[196:199], v[70:73]
	v_mfma_f32_16x16x32_bf16 v[118:121], v[160:163], v[176:179], v[118:121]
	v_mfma_f32_16x16x32_bf16 v[110:113], v[168:171], v[176:179], v[110:113]
	v_mfma_f32_16x16x32_bf16 v[102:105], v[160:163], v[184:187], v[102:105]
	v_mfma_f32_16x16x32_bf16 v[94:97], v[168:171], v[184:187], v[94:97]
	v_mfma_f32_16x16x32_bf16 v[86:89], v[160:163], v[192:195], v[86:89]
	v_mfma_f32_16x16x32_bf16 v[78:81], v[168:171], v[192:195], v[78:81]
	v_mfma_f32_16x16x32_bf16 v[74:77], v[160:163], v[200:203], v[74:77]
	v_mfma_f32_16x16x32_bf16 v[70:73], v[168:171], v[200:203], v[70:73]
	s_setprio 0
	s_barrier
	s_add_i32 s48, s50, s29
	v_lshl_add_u64 v[204:205], s[24:25], 0, v[134:135]
	s_mov_b32 m0, s48
	ds_read_b128 v[172:175], v5 offset:16384
	ds_read_b128 v[176:179], v5 offset:17408
	ds_read_b128 v[180:183], v5 offset:18432
	ds_read_b128 v[184:187], v5 offset:19456
	ds_read_b128 v[188:191], v5 offset:20480
	ds_read_b128 v[192:195], v5 offset:21504
	ds_read_b128 v[196:199], v5 offset:22528
	ds_read_b128 v[200:203], v5 offset:23552
	global_load_lds_dwordx4 v[204:205], off
	s_add_i32 m0, s48, 0x2000
	v_lshl_add_u64 v[204:205], s[24:25], 0, v[138:139]
	s_add_u32 s24, s24, 0x20000
	s_addc_u32 s25, s25, 0
	s_add_i32 s48, s51, s29
	global_load_lds_dwordx4 v[204:205], off
	v_lshl_add_u64 v[204:205], s[24:25], 0, v[134:135]
	s_mov_b32 m0, s48
	s_nop 0
	global_load_lds_dwordx4 v[204:205], off
	v_lshl_add_u64 v[204:205], s[24:25], 0, v[138:139]
	s_add_i32 m0, s48, 0x2000
	s_nop 0
	global_load_lds_dwordx4 v[204:205], off
	v_lshl_add_u64 v[204:205], s[22:23], 0, v[2:3]
	s_mov_b32 m0, s15
	s_nop 0
	global_load_lds_dwordx4 v[204:205], off
	v_lshl_add_u64 v[204:205], s[22:23], 0, v[136:137]
	s_mov_b32 m0, s17
	s_nop 0
	global_load_lds_dwordx4 v[204:205], off
	s_waitcnt vmcnt(8)
	s_waitcnt lgkmcnt(0)
	s_barrier
	s_setprio 1
	s_waitcnt lgkmcnt(0)
	v_mfma_f32_16x16x32_bf16 v[66:69], v[140:143], v[172:175], v[66:69]
	v_mfma_f32_16x16x32_bf16 v[62:65], v[148:151], v[172:175], v[62:65]
	v_mfma_f32_16x16x32_bf16 v[58:61], v[140:143], v[180:183], v[58:61]
	v_mfma_f32_16x16x32_bf16 v[50:53], v[148:151], v[180:183], v[50:53]
	v_mfma_f32_16x16x32_bf16 v[42:45], v[140:143], v[188:191], v[42:45]
	v_mfma_f32_16x16x32_bf16 v[34:37], v[148:151], v[188:191], v[34:37]
	v_mfma_f32_16x16x32_bf16 v[26:29], v[140:143], v[196:199], v[26:29]
	v_mfma_f32_16x16x32_bf16 v[18:21], v[148:151], v[196:199], v[18:21]
	v_mfma_f32_16x16x32_bf16 v[66:69], v[144:147], v[176:179], v[66:69]
	v_mfma_f32_16x16x32_bf16 v[62:65], v[152:155], v[176:179], v[62:65]
	v_mfma_f32_16x16x32_bf16 v[58:61], v[144:147], v[184:187], v[58:61]
	v_mfma_f32_16x16x32_bf16 v[50:53], v[152:155], v[184:187], v[50:53]
	v_mfma_f32_16x16x32_bf16 v[42:45], v[144:147], v[192:195], v[42:45]
	v_mfma_f32_16x16x32_bf16 v[34:37], v[152:155], v[192:195], v[34:37]
	v_mfma_f32_16x16x32_bf16 v[26:29], v[144:147], v[200:203], v[26:29]
	v_mfma_f32_16x16x32_bf16 v[18:21], v[152:155], v[200:203], v[18:21]
	s_setprio 0
	s_setprio 1
	v_mfma_f32_16x16x32_bf16 v[54:57], v[156:159], v[172:175], v[54:57]
	v_mfma_f32_16x16x32_bf16 v[46:49], v[164:167], v[172:175], v[46:49]
	v_mfma_f32_16x16x32_bf16 v[38:41], v[156:159], v[180:183], v[38:41]
	v_mfma_f32_16x16x32_bf16 v[30:33], v[164:167], v[180:183], v[30:33]
	v_mfma_f32_16x16x32_bf16 v[22:25], v[156:159], v[188:191], v[22:25]
	v_mfma_f32_16x16x32_bf16 v[14:17], v[164:167], v[188:191], v[14:17]
	v_mfma_f32_16x16x32_bf16 v[10:13], v[156:159], v[196:199], v[10:13]
	v_mfma_f32_16x16x32_bf16 v[6:9], v[164:167], v[196:199], v[6:9]
	v_mfma_f32_16x16x32_bf16 v[54:57], v[160:163], v[176:179], v[54:57]
	v_mfma_f32_16x16x32_bf16 v[46:49], v[168:171], v[176:179], v[46:49]
	v_mfma_f32_16x16x32_bf16 v[38:41], v[160:163], v[184:187], v[38:41]
	v_mfma_f32_16x16x32_bf16 v[30:33], v[168:171], v[184:187], v[30:33]
	v_mfma_f32_16x16x32_bf16 v[22:25], v[160:163], v[192:195], v[22:25]
	v_mfma_f32_16x16x32_bf16 v[14:17], v[168:171], v[192:195], v[14:17]
	v_mfma_f32_16x16x32_bf16 v[10:13], v[160:163], v[200:203], v[10:13]
	v_mfma_f32_16x16x32_bf16 v[6:9], v[168:171], v[200:203], v[6:9]
	s_setprio 0
	s_barrier
	s_add_i32 s24, 0, 0x18000
	s_add_i32 s25, 0, 0x1c000
	v_add_u32_e32 v152, s24, v1
	v_add_u32_e32 v168, s25, v1
	ds_read_b128 v[140:143], v152
	ds_read_b128 v[144:147], v152 offset:1024
	ds_read_b128 v[148:151], v152 offset:2048
	ds_read_b128 v[152:155], v152 offset:3072
	ds_read_b128 v[156:159], v168
	ds_read_b128 v[160:163], v168 offset:1024
	ds_read_b128 v[164:167], v168 offset:2048
	ds_read_b128 v[168:171], v168 offset:3072
	s_add_u32 s22, s22, 0x20000
	s_addc_u32 s23, s23, 0
	s_mov_b32 m0, s31
	v_lshl_add_u64 v[204:205], s[22:23], 0, v[2:3]
	ds_read_b128 v[172:175], v5 offset:32768
	ds_read_b128 v[176:179], v5 offset:33792
	ds_read_b128 v[180:183], v5 offset:34816
	ds_read_b128 v[184:187], v5 offset:35840
	ds_read_b128 v[188:191], v5 offset:36864
	ds_read_b128 v[192:195], v5 offset:37888
	ds_read_b128 v[196:199], v5 offset:38912
	ds_read_b128 v[200:203], v5 offset:39936
	global_load_lds_dwordx4 v[204:205], off
	v_lshl_add_u64 v[204:205], s[22:23], 0, v[136:137]
	s_mov_b32 m0, s33
	s_nop 0
	global_load_lds_dwordx4 v[204:205], off
	s_waitcnt vmcnt(8)
	s_waitcnt lgkmcnt(0)
	s_barrier
	s_setprio 1
	s_waitcnt lgkmcnt(0)
	v_mfma_f32_16x16x32_bf16 v[130:133], v[140:143], v[172:175], v[130:133]
	v_mfma_f32_16x16x32_bf16 v[126:129], v[148:151], v[172:175], v[126:129]
	v_mfma_f32_16x16x32_bf16 v[122:125], v[140:143], v[180:183], v[122:125]
	v_mfma_f32_16x16x32_bf16 v[114:117], v[148:151], v[180:183], v[114:117]
	v_mfma_f32_16x16x32_bf16 v[106:109], v[140:143], v[188:191], v[106:109]
	v_mfma_f32_16x16x32_bf16 v[98:101], v[148:151], v[188:191], v[98:101]
	v_mfma_f32_16x16x32_bf16 v[90:93], v[140:143], v[196:199], v[90:93]
	v_mfma_f32_16x16x32_bf16 v[82:85], v[148:151], v[196:199], v[82:85]
	v_mfma_f32_16x16x32_bf16 v[130:133], v[144:147], v[176:179], v[130:133]
	v_mfma_f32_16x16x32_bf16 v[126:129], v[152:155], v[176:179], v[126:129]
	v_mfma_f32_16x16x32_bf16 v[122:125], v[144:147], v[184:187], v[122:125]
	v_mfma_f32_16x16x32_bf16 v[114:117], v[152:155], v[184:187], v[114:117]
	v_mfma_f32_16x16x32_bf16 v[106:109], v[144:147], v[192:195], v[106:109]
	v_mfma_f32_16x16x32_bf16 v[98:101], v[152:155], v[192:195], v[98:101]
	v_mfma_f32_16x16x32_bf16 v[90:93], v[144:147], v[200:203], v[90:93]
	v_mfma_f32_16x16x32_bf16 v[82:85], v[152:155], v[200:203], v[82:85]
	s_setprio 0
	s_setprio 1
	v_mfma_f32_16x16x32_bf16 v[118:121], v[156:159], v[172:175], v[118:121]
	v_mfma_f32_16x16x32_bf16 v[110:113], v[164:167], v[172:175], v[110:113]
	v_mfma_f32_16x16x32_bf16 v[102:105], v[156:159], v[180:183], v[102:105]
	v_mfma_f32_16x16x32_bf16 v[94:97], v[164:167], v[180:183], v[94:97]
	v_mfma_f32_16x16x32_bf16 v[86:89], v[156:159], v[188:191], v[86:89]
	v_mfma_f32_16x16x32_bf16 v[78:81], v[164:167], v[188:191], v[78:81]
	v_mfma_f32_16x16x32_bf16 v[74:77], v[156:159], v[196:199], v[74:77]
	v_mfma_f32_16x16x32_bf16 v[70:73], v[164:167], v[196:199], v[70:73]
	v_mfma_f32_16x16x32_bf16 v[118:121], v[160:163], v[176:179], v[118:121]
	v_mfma_f32_16x16x32_bf16 v[110:113], v[168:171], v[176:179], v[110:113]
	v_mfma_f32_16x16x32_bf16 v[102:105], v[160:163], v[184:187], v[102:105]
	v_mfma_f32_16x16x32_bf16 v[94:97], v[168:171], v[184:187], v[94:97]
	v_mfma_f32_16x16x32_bf16 v[86:89], v[160:163], v[192:195], v[86:89]
	v_mfma_f32_16x16x32_bf16 v[78:81], v[168:171], v[192:195], v[78:81]
	v_mfma_f32_16x16x32_bf16 v[74:77], v[160:163], v[200:203], v[74:77]
	v_mfma_f32_16x16x32_bf16 v[70:73], v[168:171], v[200:203], v[70:73]
	s_setprio 0
	s_barrier
	s_add_i32 s22, s24, s29
	v_lshl_add_u64 v[204:205], s[20:21], 0, v[134:135]
	s_mov_b32 m0, s22
	ds_read_b128 v[172:175], v5 offset:49152
	ds_read_b128 v[176:179], v5 offset:50176
	ds_read_b128 v[180:183], v5 offset:51200
	ds_read_b128 v[184:187], v5 offset:52224
	ds_read_b128 v[188:191], v5 offset:53248
	ds_read_b128 v[192:195], v5 offset:54272
	ds_read_b128 v[196:199], v5 offset:55296
	ds_read_b128 v[200:203], v5 offset:56320
	global_load_lds_dwordx4 v[204:205], off
	s_add_i32 m0, s22, 0x2000
	v_lshl_add_u64 v[204:205], s[20:21], 0, v[138:139]
	s_add_u32 s20, s20, 0x20000
	s_addc_u32 s21, s21, 0
	s_add_i32 s22, s25, s29
	global_load_lds_dwordx4 v[204:205], off
	v_lshl_add_u64 v[204:205], s[20:21], 0, v[134:135]
	s_mov_b32 m0, s22
	s_nop 0
	global_load_lds_dwordx4 v[204:205], off
	v_lshl_add_u64 v[204:205], s[20:21], 0, v[138:139]
	s_add_i32 m0, s22, 0x2000
	s_nop 0
	global_load_lds_dwordx4 v[204:205], off
	v_lshl_add_u64 v[204:205], s[18:19], 0, v[2:3]
	s_mov_b32 m0, s38
	s_nop 0
	global_load_lds_dwordx4 v[204:205], off
	v_lshl_add_u64 v[204:205], s[18:19], 0, v[136:137]
	s_mov_b32 m0, s39
	s_nop 0
	global_load_lds_dwordx4 v[204:205], off
	s_waitcnt vmcnt(8)
	s_waitcnt lgkmcnt(0)
	s_barrier
	s_setprio 1
	s_waitcnt lgkmcnt(0)
	v_mfma_f32_16x16x32_bf16 v[66:69], v[140:143], v[172:175], v[66:69]
	v_mfma_f32_16x16x32_bf16 v[62:65], v[148:151], v[172:175], v[62:65]
	v_mfma_f32_16x16x32_bf16 v[58:61], v[140:143], v[180:183], v[58:61]
	v_mfma_f32_16x16x32_bf16 v[50:53], v[148:151], v[180:183], v[50:53]
	v_mfma_f32_16x16x32_bf16 v[42:45], v[140:143], v[188:191], v[42:45]
	v_mfma_f32_16x16x32_bf16 v[34:37], v[148:151], v[188:191], v[34:37]
	v_mfma_f32_16x16x32_bf16 v[26:29], v[140:143], v[196:199], v[26:29]
	v_mfma_f32_16x16x32_bf16 v[18:21], v[148:151], v[196:199], v[18:21]
	v_mfma_f32_16x16x32_bf16 v[66:69], v[144:147], v[176:179], v[66:69]
	v_mfma_f32_16x16x32_bf16 v[62:65], v[152:155], v[176:179], v[62:65]
	v_mfma_f32_16x16x32_bf16 v[58:61], v[144:147], v[184:187], v[58:61]
	v_mfma_f32_16x16x32_bf16 v[50:53], v[152:155], v[184:187], v[50:53]
	v_mfma_f32_16x16x32_bf16 v[42:45], v[144:147], v[192:195], v[42:45]
	v_mfma_f32_16x16x32_bf16 v[34:37], v[152:155], v[192:195], v[34:37]
	v_mfma_f32_16x16x32_bf16 v[26:29], v[144:147], v[200:203], v[26:29]
	v_mfma_f32_16x16x32_bf16 v[18:21], v[152:155], v[200:203], v[18:21]
	s_setprio 0
	s_setprio 1
	v_mfma_f32_16x16x32_bf16 v[54:57], v[156:159], v[172:175], v[54:57]
	v_mfma_f32_16x16x32_bf16 v[46:49], v[164:167], v[172:175], v[46:49]
	v_mfma_f32_16x16x32_bf16 v[38:41], v[156:159], v[180:183], v[38:41]
	v_mfma_f32_16x16x32_bf16 v[30:33], v[164:167], v[180:183], v[30:33]
	v_mfma_f32_16x16x32_bf16 v[22:25], v[156:159], v[188:191], v[22:25]
	v_mfma_f32_16x16x32_bf16 v[14:17], v[164:167], v[188:191], v[14:17]
	v_mfma_f32_16x16x32_bf16 v[10:13], v[156:159], v[196:199], v[10:13]
	v_mfma_f32_16x16x32_bf16 v[6:9], v[164:167], v[196:199], v[6:9]
	v_mfma_f32_16x16x32_bf16 v[54:57], v[160:163], v[176:179], v[54:57]
	v_mfma_f32_16x16x32_bf16 v[46:49], v[168:171], v[176:179], v[46:49]
	v_mfma_f32_16x16x32_bf16 v[38:41], v[160:163], v[184:187], v[38:41]
	v_mfma_f32_16x16x32_bf16 v[30:33], v[168:171], v[184:187], v[30:33]
	v_mfma_f32_16x16x32_bf16 v[22:25], v[160:163], v[192:195], v[22:25]
	v_mfma_f32_16x16x32_bf16 v[14:17], v[168:171], v[192:195], v[14:17]
	v_mfma_f32_16x16x32_bf16 v[10:13], v[160:163], v[200:203], v[10:13]
	v_mfma_f32_16x16x32_bf16 v[6:9], v[168:171], v[200:203], v[6:9]
	s_setprio 0
	s_barrier
	s_add_i32 s47, s47, 2
	s_add_u32 s43, s43, 0x100
	s_addc_u32 s44, s44, 0
	s_add_u32 s45, s45, 0x100
	s_addc_u32 s46, s46, 0
	s_cmp_gt_u32 s47, 5
	s_cbranch_scc0 .LBB0_536
	s_lshl_b32 s20, s16, 8
	v_mov_b32_e32 v140, v0
	s_mov_b64 s[18:19], s[84:85]
	s_lshl_b32 s7, s14, 8
	s_ashr_i32 s21, s20, 31
	s_add_i32 s7, s7, s34
	s_lshl_b64 s[20:21], s[20:21], 1
	v_and_b32_e32 v142, 15, v140
	s_add_u32 s18, s18, s20
	v_or_b32_e32 v146, s7, v142
	v_lshrrev_b32_e32 v140, 1, v140
	s_addc_u32 s19, s19, s21
	s_ashr_i32 s9, s7, 11
	v_mov_b32_e32 v143, s7
	s_movk_i32 s7, 0x7cf
	v_and_or_b32 v140, v140, 24, s35
	s_mulk_i32 s9, 0x810
	v_bitop3_b32 v142, v142, s7, v143 bitop3:0xc8
	v_lshlrev_b32_e32 v140, 1, v140
	v_mov_b32_e32 v141, v4
	v_add_u32_e32 v142, s9, v142
	v_lshl_add_u64 v[140:141], s[18:19], 0, v[140:141]
	s_mov_b64 s[18:19], 0x2c900000
	v_ashrrev_i32_e32 v143, 31, v142
	v_lshl_add_u64 v[140:141], v[140:141], 0, s[18:19]
	v_lshlrev_b64 v[144:145], 13, v[142:143]
	v_lshl_add_u64 v[144:145], v[140:141], 0, v[144:145]
	v_cvt_pk_bf16_f32 v130, v130, v131
	v_cvt_pk_bf16_f32 v131, v132, v133
	v_cvt_pk_bf16_f32 v132, v126, v127
	v_cvt_pk_bf16_f32 v133, v128, v129
	global_store_dwordx4 v[144:145], v[130:133], off
	v_cvt_pk_bf16_f32 v118, v118, v119
	v_cvt_pk_bf16_f32 v119, v120, v121
	v_cvt_pk_bf16_f32 v120, v110, v111
	v_add_u32_e32 v110, 16, v142
	v_ashrrev_i32_e32 v111, 31, v110
	v_lshlrev_b64 v[110:111], 13, v[110:111]
	v_cvt_pk_bf16_f32 v121, v112, v113
	global_store_dwordx4 v[144:145], v[118:121], off offset:256
	s_movk_i32 s7, 0x810
	s_and_b64 vcc, exec, s[0:1]
	v_lshl_add_u64 v[118:119], v[140:141], 0, v[110:111]
	v_cvt_pk_bf16_f32 v110, v122, v123
	v_cvt_pk_bf16_f32 v111, v124, v125
	v_cvt_pk_bf16_f32 v112, v114, v115
	v_cvt_pk_bf16_f32 v113, v116, v117
	global_store_dwordx4 v[118:119], v[110:113], off
	v_cvt_pk_bf16_f32 v102, v102, v103
	v_cvt_pk_bf16_f32 v103, v104, v105
	v_cvt_pk_bf16_f32 v104, v94, v95
	v_add_u32_e32 v94, 32, v142
	v_ashrrev_i32_e32 v95, 31, v94
	v_lshlrev_b64 v[94:95], 13, v[94:95]
	v_cvt_pk_bf16_f32 v105, v96, v97
	global_store_dwordx4 v[118:119], v[102:105], off offset:256
	s_mov_b32 s16, s8
	s_mov_b32 s14, s6
	v_lshl_add_u64 v[102:103], v[140:141], 0, v[94:95]
	v_cvt_pk_bf16_f32 v94, v106, v107
	v_cvt_pk_bf16_f32 v95, v108, v109
	v_cvt_pk_bf16_f32 v96, v98, v99
	v_cvt_pk_bf16_f32 v97, v100, v101
	global_store_dwordx4 v[102:103], v[94:97], off
	v_cvt_pk_bf16_f32 v86, v86, v87
	v_cvt_pk_bf16_f32 v87, v88, v89
	v_cvt_pk_bf16_f32 v88, v78, v79
	v_add_u32_e32 v78, 48, v142
	v_ashrrev_i32_e32 v79, 31, v78
	v_lshlrev_b64 v[78:79], 13, v[78:79]
	v_cvt_pk_bf16_f32 v89, v80, v81
	global_store_dwordx4 v[102:103], v[86:89], off offset:256
	s_mov_b64 s[20:21], s[10:11]
	s_mov_b64 s[18:19], s[12:13]
	v_lshl_add_u64 v[86:87], v[140:141], 0, v[78:79]
	v_cvt_pk_bf16_f32 v78, v90, v91
	v_cvt_pk_bf16_f32 v79, v92, v93
	v_cvt_pk_bf16_f32 v80, v82, v83
	v_cvt_pk_bf16_f32 v81, v84, v85
	global_store_dwordx4 v[86:87], v[78:81], off
	v_cvt_pk_bf16_f32 v74, v74, v75
	v_cvt_pk_bf16_f32 v75, v76, v77
	v_cvt_pk_bf16_f32 v76, v70, v71
	v_add_u32_e32 v70, 0x80, v146
	v_ashrrev_i32_e32 v71, 11, v70
	v_and_b32_e32 v70, 0x7cf, v70
	v_mad_i32_i24 v70, v71, s7, v70
	v_ashrrev_i32_e32 v71, 31, v70
	v_cvt_pk_bf16_f32 v77, v72, v73
	v_lshlrev_b64 v[72:73], 13, v[70:71]
	global_store_dwordx4 v[86:87], v[74:77], off offset:256
	v_lshl_add_u64 v[72:73], v[140:141], 0, v[72:73]
	v_cvt_pk_bf16_f32 v66, v66, v67
	v_cvt_pk_bf16_f32 v67, v68, v69
	v_cvt_pk_bf16_f32 v68, v62, v63
	v_cvt_pk_bf16_f32 v69, v64, v65
	global_store_dwordx4 v[72:73], v[66:69], off
	v_cvt_pk_bf16_f32 v54, v54, v55
	v_cvt_pk_bf16_f32 v55, v56, v57
	v_cvt_pk_bf16_f32 v56, v46, v47
	v_add_u32_e32 v46, 16, v70
	v_ashrrev_i32_e32 v47, 31, v46
	v_lshlrev_b64 v[46:47], 13, v[46:47]
	v_cvt_pk_bf16_f32 v57, v48, v49
	global_store_dwordx4 v[72:73], v[54:57], off offset:256
	s_mov_b32 s51, 0x40c000
	s_mov_b32 s47, 0x120000
	v_lshl_add_u64 v[54:55], v[140:141], 0, v[46:47]
	v_cvt_pk_bf16_f32 v46, v58, v59
	v_cvt_pk_bf16_f32 v47, v60, v61
	v_cvt_pk_bf16_f32 v48, v50, v51
	v_cvt_pk_bf16_f32 v49, v52, v53
	global_store_dwordx4 v[54:55], v[46:49], off
	v_cvt_pk_bf16_f32 v38, v38, v39
	v_cvt_pk_bf16_f32 v39, v40, v41
	v_cvt_pk_bf16_f32 v40, v30, v31
	v_add_u32_e32 v30, 32, v70
	v_ashrrev_i32_e32 v31, 31, v30
	v_lshlrev_b64 v[30:31], 13, v[30:31]
	v_cvt_pk_bf16_f32 v41, v32, v33
	global_store_dwordx4 v[54:55], v[38:41], off offset:256
	s_mov_b64 s[48:49], 0x7ffff
	s_nop 0
	v_lshl_add_u64 v[38:39], v[140:141], 0, v[30:31]
	v_cvt_pk_bf16_f32 v30, v42, v43
	v_cvt_pk_bf16_f32 v31, v44, v45
	v_cvt_pk_bf16_f32 v32, v34, v35
	v_cvt_pk_bf16_f32 v33, v36, v37
	global_store_dwordx4 v[38:39], v[30:33], off
	v_cvt_pk_bf16_f32 v22, v22, v23
	v_cvt_pk_bf16_f32 v23, v24, v25
	v_cvt_pk_bf16_f32 v24, v14, v15
	v_add_u32_e32 v14, 48, v70
	v_ashrrev_i32_e32 v15, 31, v14
	v_lshlrev_b64 v[14:15], 13, v[14:15]
	v_cvt_pk_bf16_f32 v25, v16, v17
	global_store_dwordx4 v[38:39], v[22:25], off offset:256
	s_nop 1
	v_lshl_add_u64 v[22:23], v[140:141], 0, v[14:15]
	v_cvt_pk_bf16_f32 v14, v26, v27
	v_cvt_pk_bf16_f32 v15, v28, v29
	v_cvt_pk_bf16_f32 v16, v18, v19
	v_cvt_pk_bf16_f32 v17, v20, v21
	global_store_dwordx4 v[22:23], v[14:17], off
	v_cvt_pk_bf16_f32 v10, v10, v11
	v_cvt_pk_bf16_f32 v11, v12, v13
	v_cvt_pk_bf16_f32 v12, v6, v7
	v_cvt_pk_bf16_f32 v13, v8, v9
	global_store_dwordx4 v[22:23], v[10:13], off offset:256
	s_cbranch_vccz .LBB0_529
	s_waitcnt vmcnt(0)
	s_cmpk_gt_u32 s28, 0xff
	s_cbranch_scc1 .LBB0_540
	s_barrier
